# batched the serialized load-wait-add-store chains of the two residual epilogues (4 loads in flight, counted vmcnt), batched mini-GEMM operand loads, per-lane lambda dot with wave reduction
# speedup vs baseline: 1.0099x; 1.0099x over previous
; DEV void phase_O(const Params& p, int layer, int qidx, unsigned char* ldsraw) {
;     ...
;   const float* lp = p.in[7] + layer * 256;
;   float d0 = 0.f, d1 = 0.f;
;   for (int i = 0; i < 64; i++) { d0 += lp[i] * lp[64 + i]; d1 += lp[128 + i] * lp[192 + i]; }
;   int ly = layer; asm volatile("" : "+s"(ly));
;   const float li = (ly == 0) ? 0.2f : 0.35550906759f;
;   const float lam = __uint_as_float(__builtin_amdgcn_readfirstlane(__float_as_uint(__expf(d0) - __expf(d1) + li)));
.Llam_dot:
	s_mov_b32 s2, s21
	s_mov_b32 s3, s22
	v_mbcnt_lo_u32_b32 v4, -1, 0
	v_mbcnt_hi_u32_b32 v4, -1, v4
	v_lshlrev_b32_e32 v5, 2, v4
	global_load_dword v6, v5, s[2:3]
	global_load_dword v7, v5, s[2:3] offset:256
	global_load_dword v8, v5, s[2:3] offset:512
	global_load_dword v9, v5, s[2:3] offset:768
	s_waitcnt vmcnt(0)
	v_mul_f32_e32 v2, v6, v7
	v_mul_f32_e32 v3, v8, v9
	v_xor_b32_e32 v10, 4, v5
	ds_bpermute_b32 v11, v10, v2
	ds_bpermute_b32 v12, v10, v3
	s_waitcnt lgkmcnt(0)
	v_add_f32_e32 v2, v2, v11
	v_add_f32_e32 v3, v3, v12
	v_xor_b32_e32 v10, 8, v5
	ds_bpermute_b32 v11, v10, v2
	ds_bpermute_b32 v12, v10, v3
	s_waitcnt lgkmcnt(0)
	v_add_f32_e32 v2, v2, v11
	v_add_f32_e32 v3, v3, v12
	v_xor_b32_e32 v10, 16, v5
	ds_bpermute_b32 v11, v10, v2
	ds_bpermute_b32 v12, v10, v3
	s_waitcnt lgkmcnt(0)
	v_add_f32_e32 v2, v2, v11
	v_add_f32_e32 v3, v3, v12
	v_xor_b32_e32 v10, 32, v5
	ds_bpermute_b32 v11, v10, v2
	ds_bpermute_b32 v12, v10, v3
	s_waitcnt lgkmcnt(0)
	v_add_f32_e32 v2, v2, v11
	v_add_f32_e32 v3, v3, v12
	v_xor_b32_e32 v10, 64, v5
	ds_bpermute_b32 v11, v10, v2
	ds_bpermute_b32 v12, v10, v3
	s_waitcnt lgkmcnt(0)
	v_add_f32_e32 v2, v2, v11
	v_add_f32_e32 v3, v3, v12
	v_xor_b32_e32 v10, 128, v5
	ds_bpermute_b32 v11, v10, v2
	ds_bpermute_b32 v12, v10, v3
	s_waitcnt lgkmcnt(0)
	v_add_f32_e32 v2, v2, v11
	v_add_f32_e32 v3, v3, v12
	v_readlane_b32 s0, v255, 20
	v_readlane_b32 s1, v255, 27
	s_or_b32 s82, s1, s0
	s_lshl_b64 s[0:1], s[82:83], 2
	v_readlane_b32 s2, v254, 47
	v_mul_f32_e32 v0, 0x3fb8aa3b, v2
	v_mul_f32_e32 v2, 0x3fb8aa3b, v3
	s_add_u32 s64, s2, s0
	v_readlane_b32 s0, v254, 48
	v_exp_f32_e32 v0, v0
	v_exp_f32_e32 v2, v2
	s_addc_u32 s65, s0, s1
	v_readlane_b32 s0, v255, 10
	s_cmp_eq_u32 s0, 0
	s_cselect_b64 vcc, -1, 0
	v_mov_b32_e32 v3, 0x3eb60549
	v_mov_b32_e32 v4, 0x3e4ccccd
	v_cndmask_b32_e32 v3, v3, v4, vcc
	v_sub_f32_e32 v0, v0, v2
	v_add_f32_e32 v0, v0, v3
	s_nop 0
	v_readfirstlane_b32 s50, v0
	v_mov_b32_e32 v0, v181
	s_mov_b32 s51, s50
	v_cmp_eq_u32_e64 s[4:5], 0, v0
	s_branch .LBB0_671

; #define MFMA(a, b, c) __builtin_amdgcn_mfma_f32_16x16x32_bf16(a, b, c, 0, 0, 0)
; DEV int get_tid() { int t = threadIdx.x; asm volatile("" : "+v"(t)); return t; }
; DEV float bf2f(bf16_t h) { return __uint_as_float(((unsigned)h) << 16); }
; DEV uint2 pack4(f32x4 v) { uint2 r; r.x = pack2(v[0], v[1]); r.y = pack2(v[2], v[3]); return r; }
; DEV f32x4 mini_gemm16(const bf16_t* __restrict__ A16, int lda, const bf16_t* __restrict__ Bt16, int ldb, int k0, int klen, int lane) {
;   const int lr = lane & 15, lg = lane >> 4;
;   const bf16_t* pa = A16 + (size_t)lr * lda + k0 + lg * 8;
;   const bf16_t* pb = Bt16 + (size_t)lr * ldb + k0 + lg * 8;
;   f32x4 acc = (f32x4){0.f, 0.f, 0.f, 0.f};
; #pragma unroll 4
;   for (int k = 0; k < klen; k += 32) {
;     bf16x8 a = *(const bf16x8*)(pa + k);
;     bf16x8 b = *(const bf16x8*)(pb + k);
;     acc = MFMA(b, a, acc);
;   }
;   return acc;
; DEV void phase_Y(const Params& p, unsigned char* ldsraw) {
;     ...
;   for (int item = vblock(); item < 32 * 8 + 64; item += gridDim.x) {
;     if (item >= 256) {
;       const int lane = get_tid() & 63, wave = get_tid() >> 6, lr = lane & 15, lg = lane >> 4;
;       const int n0 = (item - 256) * 16;
;       f32x4* red = (f32x4*)ldsraw;
;       __syncthreads();
; #pragma unroll 1
;       for (int br = 0; br < 3; br++) {
;         const bf16_t* Ab = (const bf16_t*)(ws + (br == 0 ? OFF_ORET : (br == 1 ? OFF_OHG : OFF_ODA))) + (size_t)112 * 1024;
;         red[(br * 8 + wave) * 64 + lane] = mini_gemm16(Ab, 1024, WB + ((size_t)br * 1024 + n0) * 1024, 1024, wave * 128, 128, lane);
;       }
;       __syncthreads();
;       if (wave == 0) {
;         f32x4 y = (f32x4){0.f, 0.f, 0.f, 0.f};
; #pragma unroll
;         for (int br = 0; br < 3; br++) {
;           f32x4 a = red[(br * 8) * 64 + lane];
; #pragma unroll
;           for (int w = 1; w < 8; w++) a += red[(br * 8 + w) * 64 + lane];
;           uint2 gv = *(const uint2*)(G + (size_t)(112 + lr) * 3072 + br * 1024 + n0 + lg * 4);
;           y[0] += bf2f((bf16_t)(gv.x & 0xffff)) * a[0];
;           y[1] += bf2f((bf16_t)(gv.x >> 16)) * a[1];
;           y[2] += bf2f((bf16_t)(gv.y & 0xffff)) * a[2];
;           y[3] += bf2f((bf16_t)(gv.y >> 16)) * a[3];
;         }
;         *(uint2*)(Y + (size_t)(112 + lr) * 1024 + n0 + lg * 4) = pack4(y);
;       }
;       continue;
.LBB0_984:
	s_cmpk_eq_i32 s0, 0x2000
	s_cselect_b32 s1, s69, 0xc3bb700
	s_cmp_lg_u32 s0, 0
	s_cselect_b32 s1, s1, 0x114fb700
	s_add_u32 s4, s92, s1
	s_addc_u32 s5, s93, 0
	v_lshl_add_u64 v[14:15], s[4:5], 0, v[0:1]
	v_lshl_add_u64 v[14:15], v[4:5], 1, v[14:15]
	v_mov_b32_e32 v9, v1
	v_lshl_add_u64 v[14:15], v[14:15], 0, v[8:9]
	s_mov_b64 s[4:5], 0x38000
	s_mov_b32 s1, 0x38000
	v_lshl_add_u64 v[26:27], v[14:15], 0, s[4:5]
	v_add_co_u32_e32 v14, vcc, s1, v14
	s_lshl_b64 s[6:7], s[82:83], 11
	s_nop 0
	v_addc_co_u32_e32 v15, vcc, 0, v15, vcc
	v_lshl_add_u64 v[28:29], v[6:7], 0, s[6:7]
	global_load_dwordx4 v[60:63], v[14:15], off
	global_load_dwordx4 v[64:67], v[28:29], off
	global_load_dwordx4 v[68:71], v[26:27], off offset:64
	global_load_dwordx4 v[72:75], v[28:29], off offset:64
	global_load_dwordx4 v[76:79], v[26:27], off offset:128
	global_load_dwordx4 v[80:83], v[28:29], off offset:128
	global_load_dwordx4 v[84:87], v[26:27], off offset:192
	global_load_dwordx4 v[88:91], v[28:29], off offset:192
	v_add_u32_e32 v9, s0, v12
	s_addk_i32 s0, 0x2000
	s_addk_i32 s82, 0x400
	s_cmpk_eq_i32 s0, 0x6000
	s_waitcnt vmcnt(6)
	v_mfma_f32_16x16x32_bf16 v[14:17], v[64:67], v[60:63], 0
	s_waitcnt vmcnt(4)
	v_mfma_f32_16x16x32_bf16 v[14:17], v[72:75], v[68:71], v[14:17]
	s_waitcnt vmcnt(2)
	v_mfma_f32_16x16x32_bf16 v[14:17], v[80:83], v[76:79], v[14:17]
	s_waitcnt vmcnt(0)
	v_mfma_f32_16x16x32_bf16 v[14:17], v[88:91], v[84:87], v[14:17]
	s_nop 0
	s_nop 7
	ds_write_b128 v9, v[14:17]
	s_cbranch_scc0 .LBB0_984
	v_cmp_gt_u32_e32 vcc, 64, v11
	s_waitcnt lgkmcnt(0)
	s_barrier
	s_and_saveexec_b64 s[0:1], vcc
	s_cbranch_execz .LBB0_974
	v_and_b32_e32 v26, 15, v3
	s_lshl_b32 s4, s2, 4
	v_mul_u32_u24_e32 v0, 0xc00, v26
	s_add_i32 s82, s4, 0xfffff000
	v_lshlrev_b32_e32 v0, 1, v0
	v_lshl_add_u64 v[4:5], s[96:97], 0, v[0:1]
	s_lshl_b64 s[4:5], s[82:83], 1
	v_lshl_add_u32 v27, v10, 4, 0
	v_lshl_add_u64 v[4:5], v[4:5], 0, s[4:5]
	v_mov_b32_e32 v3, v1
	v_lshl_add_u64 v[12:13], v[4:5], 0, v[2:3]
	ds_read_b128 v[4:7], v27
	ds_read_b128 v[8:11], v27 offset:1024
	s_mov_b64 s[6:7], 0xa8000
	v_lshl_add_u64 v[20:21], v[12:13], 0, s[6:7]
	s_mov_b32 s6, 0xa9000
	v_add_co_u32_e32 v24, vcc, s6, v12
	s_waitcnt lgkmcnt(0)
	v_pk_add_f32 v[10:11], v[6:7], v[10:11]
	v_pk_add_f32 v[8:9], v[4:5], v[8:9]
	ds_read_b128 v[4:7], v27 offset:2048
	v_addc_co_u32_e32 v25, vcc, 0, v13, vcc
	v_lshlrev_b32_e32 v0, 11, v26
	s_waitcnt lgkmcnt(0)
	v_pk_add_f32 v[10:11], v[10:11], v[6:7]
	v_pk_add_f32 v[8:9], v[8:9], v[4:5]
	ds_read_b128 v[4:7], v27 offset:3072
	s_waitcnt lgkmcnt(0)
	v_pk_add_f32 v[10:11], v[10:11], v[6:7]
	v_pk_add_f32 v[8:9], v[8:9], v[4:5]
	ds_read_b128 v[4:7], v27 offset:4096
	s_waitcnt lgkmcnt(0)
	v_pk_add_f32 v[10:11], v[10:11], v[6:7]
	v_pk_add_f32 v[8:9], v[8:9], v[4:5]
	ds_read_b128 v[4:7], v27 offset:5120
	s_waitcnt lgkmcnt(0)
	v_pk_add_f32 v[10:11], v[10:11], v[6:7]
	v_pk_add_f32 v[8:9], v[8:9], v[4:5]
	ds_read_b128 v[4:7], v27 offset:6144
	s_waitcnt lgkmcnt(0)
	v_pk_add_f32 v[10:11], v[10:11], v[6:7]
	v_pk_add_f32 v[14:15], v[8:9], v[4:5]
	ds_read_b128 v[6:9], v27 offset:7168
	s_waitcnt lgkmcnt(0)
	v_pk_add_f32 v[4:5], v[10:11], v[8:9]
	v_pk_add_f32 v[6:7], v[14:15], v[6:7]
	global_load_dwordx2 v[8:9], v[24:25], off offset:-4096
	ds_read_b128 v[12:15], v27 offset:8192
	ds_read_b128 v[16:19], v27 offset:9216
	s_waitcnt lgkmcnt(0)
	v_pk_add_f32 v[18:19], v[14:15], v[18:19]
	v_pk_add_f32 v[16:17], v[12:13], v[16:17]
	ds_read_b128 v[12:15], v27 offset:10240
	s_waitcnt lgkmcnt(0)
	v_pk_add_f32 v[18:19], v[18:19], v[14:15]
	v_pk_add_f32 v[16:17], v[16:17], v[12:13]
	ds_read_b128 v[12:15], v27 offset:11264
	s_waitcnt lgkmcnt(0)
	v_pk_add_f32 v[18:19], v[18:19], v[14:15]
	v_pk_add_f32 v[16:17], v[16:17], v[12:13]
	ds_read_b128 v[12:15], v27 offset:12288
	s_waitcnt lgkmcnt(0)
	v_pk_add_f32 v[18:19], v[18:19], v[14:15]
	v_pk_add_f32 v[16:17], v[16:17], v[12:13]
	ds_read_b128 v[12:15], v27 offset:13312
	s_waitcnt lgkmcnt(0)
	v_pk_add_f32 v[18:19], v[18:19], v[14:15]
	v_pk_add_f32 v[16:17], v[16:17], v[12:13]
	ds_read_b128 v[12:15], v27 offset:14336
	s_waitcnt lgkmcnt(0)
	v_pk_add_f32 v[18:19], v[18:19], v[14:15]
	v_pk_add_f32 v[22:23], v[16:17], v[12:13]
	ds_read_b128 v[14:17], v27 offset:15360
	s_waitcnt lgkmcnt(0)
	v_pk_add_f32 v[12:13], v[18:19], v[16:17]
	v_pk_add_f32 v[16:17], v[22:23], v[14:15]
	global_load_dwordx2 v[14:15], v[20:21], off offset:2048
	ds_read_b128 v[20:23], v27 offset:16384
	ds_read_b128 v[28:31], v27 offset:17408
	global_load_dwordx2 v[24:25], v[24:25], off
	s_waitcnt lgkmcnt(0)
	v_pk_add_f32 v[30:31], v[22:23], v[30:31]
	v_pk_add_f32 v[28:29], v[20:21], v[28:29]
	ds_read_b128 v[20:23], v27 offset:18432
	s_waitcnt lgkmcnt(0)
	v_pk_add_f32 v[30:31], v[30:31], v[22:23]
	v_pk_add_f32 v[28:29], v[28:29], v[20:21]
	ds_read_b128 v[20:23], v27 offset:19456
	s_waitcnt lgkmcnt(0)
	v_pk_add_f32 v[30:31], v[30:31], v[22:23]
	v_pk_add_f32 v[28:29], v[28:29], v[20:21]
	ds_read_b128 v[20:23], v27 offset:20480
	s_waitcnt lgkmcnt(0)
	v_pk_add_f32 v[30:31], v[30:31], v[22:23]
	v_pk_add_f32 v[28:29], v[28:29], v[20:21]
	ds_read_b128 v[20:23], v27 offset:21504
	s_waitcnt vmcnt(2)
	v_lshlrev_b32_e32 v10, 16, v8
	v_and_b32_e32 v11, 0xffff0000, v8
	v_lshlrev_b32_e32 v8, 16, v9
	v_and_b32_e32 v9, 0xffff0000, v9
	s_waitcnt lgkmcnt(0)
	v_pk_add_f32 v[30:31], v[30:31], v[22:23]
	v_pk_add_f32 v[28:29], v[28:29], v[20:21]
	ds_read_b128 v[20:23], v27 offset:22528
	v_pk_fma_f32 v[6:7], v[6:7], v[10:11], 0 op_sel_hi:[1,1,0]
	v_pk_fma_f32 v[4:5], v[4:5], v[8:9], 0 op_sel_hi:[1,1,0]
	s_waitcnt lgkmcnt(0)
	v_pk_add_f32 v[22:23], v[30:31], v[22:23]
	v_pk_add_f32 v[32:33], v[28:29], v[20:21]
	ds_read_b128 v[28:31], v27 offset:23552
	s_waitcnt lgkmcnt(0)
	v_pk_add_f32 v[20:21], v[22:23], v[30:31]
	v_pk_add_f32 v[22:23], v[32:33], v[28:29]
	s_waitcnt vmcnt(1)
	v_lshlrev_b32_e32 v18, 16, v14
	v_and_b32_e32 v19, 0xffff0000, v14
	v_lshlrev_b32_e32 v14, 16, v15
	v_and_b32_e32 v15, 0xffff0000, v15
	s_waitcnt vmcnt(0)
	v_lshlrev_b32_e32 v28, 16, v24
	v_and_b32_e32 v29, 0xffff0000, v24
	v_pk_fma_f32 v[6:7], v[16:17], v[18:19], v[6:7]
	v_lshlrev_b32_e32 v10, 16, v25
	v_and_b32_e32 v11, 0xffff0000, v25
	v_pk_fma_f32 v[4:5], v[12:13], v[14:15], v[4:5]
	v_pk_fma_f32 v[6:7], v[22:23], v[28:29], v[6:7]
	v_pk_fma_f32 v[4:5], v[20:21], v[10:11], v[4:5]
	v_cvt_pk_bf16_f32 v6, v6, v7
	v_cvt_pk_bf16_f32 v7, v4, v5
	v_lshl_add_u64 v[4:5], s[90:91], 0, v[0:1]
	v_lshl_add_u64 v[4:5], v[4:5], 0, s[4:5]
	v_lshl_add_u64 v[2:3], v[4:5], 0, v[2:3]
	v_add_co_u32_e32 v2, vcc, 0x38000, v2
	s_nop 1
	v_addc_co_u32_e32 v3, vcc, 0, v3, vcc
	global_store_dwordx2 v[2:3], v[6:7], off
	s_branch .LBB0_974

; #define MFMA(a, b, c) __builtin_amdgcn_mfma_f32_16x16x32_bf16(a, b, c, 0, 0, 0)
; template <int BN, bool TRANS>
; DEV void gemm256_kstep(f32x4 (&acc)[4][BN / 32], const bf16_t* as, const bf16_t* bs, int sw) {
;   constexpr int LS = 64, NJ = BN / 32;
;   bf16x8 a[4];
; #pragma unroll
;   for (int i = 0; i < 4; i++) a[i] = *(const bf16x8*)(as + i * 16 * LS + sw);
; #pragma unroll
;   for (int j = 0; j < NJ; j++) {
;     bf16x8 bb = *(const bf16x8*)(bs + j * 16 * LS + sw);
; #pragma unroll
;     for (int i = 0; i < 4; i++) acc[i][j] = TRANS ? MFMA(a[i], bb, acc[i][j]) : MFMA(bb, a[i], acc[i][j]);
;   }
; }
; template <int BN, bool TRANS = false>
; DEV void gemm256_acc(f32x4 (&acc)[4][BN / 32], const bf16_t* __restrict__ A, int lda, int m_valid,
;                      const bf16_t* __restrict__ Bt, int ldb, int K, bf16_t* lds) {
;     ...
;   for (int kt = 0; kt < nk; kt++) {
;     const int cur = kt & 1;
;     gemm256_kstep<BN, TRANS>(acc, As + cur * A_SZ + aoff, Bs + cur * B_SZ + boff, sw0);
;     __builtin_amdgcn_sched_barrier(0);
;     LSTORE(cur ^ 1)
;     {
;       const int kn = (kt + 2 < nk) ? kt + 2 : nk - 1;
;       GLOAD(kn * 64)
;     }
;     __builtin_amdgcn_sched_barrier(0);
;     gemm256_kstep<BN, TRANS>(acc, As + cur * A_SZ + aoff, Bs + cur * B_SZ + boff, sw1);
;     __syncthreads();
;   }
.Lg128_1047:
	s_min_u32 s5, s1, 13
	s_lshl_b32 s82, s5, 7
	s_and_b32 s5, s1, 1
	v_lshl_add_u32 v204, s5, 15, v104
	v_lshl_add_u32 v205, s5, 14, v103
	v_add_u32_e32 v204, v204, v109
	v_add_u32_e32 v205, v205, v109
	s_xor_b32 s5, s5, 1
	s_lshl_b32 s9, s5, 15
	v_lshl_add_u32 v206, s5, 14, v103
	s_lshl_b32 s5, s5, 14
	s_add_i32 s5, s5, 0x10000
	s_waitcnt lgkmcnt(3)
	v_mfma_f32_16x16x32_bf16 v[86:89], v[236:239], v[110:113], v[86:89]
	v_mfma_f32_16x16x32_bf16 v[66:69], v[236:239], v[114:117], v[66:69]
	v_mfma_f32_16x16x32_bf16 v[30:33], v[236:239], v[118:121], v[30:33]
	v_mfma_f32_16x16x32_bf16 v[14:17], v[236:239], v[122:125], v[14:17]
	ds_read_b128 v[236:239], v205
	ds_read_b128 v[220:223], v204
	v_add3_u32 v252, s9, v105, v102
	s_waitcnt vmcnt(5)
	ds_write_b128 v252, v[38:41]
	v_lshl_add_u64 v[38:39], v[90:91], 0, s[82:83]
	global_load_dwordx4 v[38:41], v[38:39], off offset:256
	s_waitcnt lgkmcnt(5)
	v_mfma_f32_16x16x32_bf16 v[82:85], v[240:243], v[110:113], v[82:85]
	v_mfma_f32_16x16x32_bf16 v[62:65], v[240:243], v[114:117], v[62:65]
	v_mfma_f32_16x16x32_bf16 v[26:29], v[240:243], v[118:121], v[26:29]
	v_mfma_f32_16x16x32_bf16 v[10:13], v[240:243], v[122:125], v[10:13]
	ds_read_b128 v[240:243], v205 offset:2048
	ds_read_b128 v[224:227], v204 offset:2048
	v_add3_u32 v252, s9, v106, v102
	s_waitcnt vmcnt(5)
	ds_write_b128 v252, v[42:45]
	v_lshl_add_u64 v[42:43], v[92:93], 0, s[82:83]
	global_load_dwordx4 v[42:45], v[42:43], off offset:256
	v_add3_u32 v252, s9, v107, v102
	s_waitcnt vmcnt(5)
	ds_write_b128 v252, v[46:49]
	v_lshl_add_u64 v[46:47], v[94:95], 0, s[82:83]
	global_load_dwordx4 v[46:49], v[46:47], off offset:256
	s_waitcnt lgkmcnt(8)
	v_mfma_f32_16x16x32_bf16 v[78:81], v[244:247], v[110:113], v[78:81]
	v_mfma_f32_16x16x32_bf16 v[58:61], v[244:247], v[114:117], v[58:61]
	v_mfma_f32_16x16x32_bf16 v[22:25], v[244:247], v[118:121], v[22:25]
	v_mfma_f32_16x16x32_bf16 v[6:9], v[244:247], v[122:125], v[6:9]
	ds_read_b128 v[244:247], v205 offset:4096
	ds_read_b128 v[228:231], v204 offset:4096
	v_add3_u32 v252, s9, v108, v102
	s_waitcnt vmcnt(5)
	ds_write_b128 v252, v[50:53]
	v_lshl_add_u64 v[50:51], v[96:97], 0, s[82:83]
	global_load_dwordx4 v[50:53], v[50:51], off offset:256
	v_add3_u32 v252, s5, v105, v102
	s_waitcnt vmcnt(5)
	ds_write_b128 v252, v[54:57]
	v_lshl_add_u64 v[54:55], v[98:99], 0, s[82:83]
	global_load_dwordx4 v[54:57], v[54:55], off offset:256
	s_waitcnt lgkmcnt(11)
	v_mfma_f32_16x16x32_bf16 v[74:77], v[248:251], v[110:113], v[74:77]
	v_mfma_f32_16x16x32_bf16 v[34:37], v[248:251], v[114:117], v[34:37]
	v_mfma_f32_16x16x32_bf16 v[18:21], v[248:251], v[118:121], v[18:21]
	v_mfma_f32_16x16x32_bf16 v[2:5], v[248:251], v[122:125], v[2:5]
	ds_read_b128 v[248:251], v205 offset:6144
	ds_read_b128 v[232:235], v204 offset:6144
	v_add3_u32 v252, s5, v106, v102
	s_waitcnt vmcnt(5)
	ds_write_b128 v252, v[70:73]
	v_lshl_add_u64 v[70:71], v[100:101], 0, s[82:83]
	global_load_dwordx4 v[70:73], v[70:71], off offset:256
	v_lshlrev_b32_e32 v203, 1, v0
	v_add3_u32 v216, v104, s9, v203
	v_add_u32_e32 v206, v206, v203
	s_waitcnt lgkmcnt(0)
	s_barrier
	ds_read_b128 v[110:113], v216
	ds_read_b128 v[114:117], v216 offset:2048
	ds_read_b128 v[118:121], v216 offset:4096
	ds_read_b128 v[122:125], v216 offset:6144
	v_mfma_f32_16x16x32_bf16 v[86:89], v[236:239], v[220:223], v[86:89]
	v_mfma_f32_16x16x32_bf16 v[66:69], v[236:239], v[224:227], v[66:69]
	v_mfma_f32_16x16x32_bf16 v[30:33], v[236:239], v[228:231], v[30:33]
	v_mfma_f32_16x16x32_bf16 v[14:17], v[236:239], v[232:235], v[14:17]
	ds_read_b128 v[236:239], v206
	v_mfma_f32_16x16x32_bf16 v[82:85], v[240:243], v[220:223], v[82:85]
	v_mfma_f32_16x16x32_bf16 v[62:65], v[240:243], v[224:227], v[62:65]
	v_mfma_f32_16x16x32_bf16 v[26:29], v[240:243], v[228:231], v[26:29]
	v_mfma_f32_16x16x32_bf16 v[10:13], v[240:243], v[232:235], v[10:13]
	ds_read_b128 v[240:243], v206 offset:2048
	v_mfma_f32_16x16x32_bf16 v[78:81], v[244:247], v[220:223], v[78:81]
	v_mfma_f32_16x16x32_bf16 v[58:61], v[244:247], v[224:227], v[58:61]
	v_mfma_f32_16x16x32_bf16 v[22:25], v[244:247], v[228:231], v[22:25]
	v_mfma_f32_16x16x32_bf16 v[6:9], v[244:247], v[232:235], v[6:9]
	ds_read_b128 v[244:247], v206 offset:4096
	v_mfma_f32_16x16x32_bf16 v[74:77], v[248:251], v[220:223], v[74:77]
	v_mfma_f32_16x16x32_bf16 v[34:37], v[248:251], v[224:227], v[34:37]
	v_mfma_f32_16x16x32_bf16 v[18:21], v[248:251], v[228:231], v[18:21]
	v_mfma_f32_16x16x32_bf16 v[2:5], v[248:251], v[232:235], v[2:5]
	ds_read_b128 v[248:251], v206 offset:6144
	s_add_i32 s1, s1, 1
	s_cmp_lg_u32 s1, 16
	s_cbranch_scc1 .Lg128_1047
; DEV int get_tid() { int t = threadIdx.x; asm volatile("" : "+v"(t)); return t; }
; DEV float* hrow(const Params& p, int b, int t) {
;   return (t < 128) ? (float*)(p.ws + OFF_H) + (size_t)(b * 128 + t) * 1024 : p.out + ((size_t)b * 8192 + (t - 128)) * 1024;
; DEV void phase_resid(const Params& p, int b, const bf16_t* A, int K, const bf16_t* Wt, unsigned char* ldsraw) {
;     ...
;     const int tid = get_tid(), lane = tid & 63, wave = tid >> 6, wm = wave >> 1, wn = wave & 1; const int lr = lane & 15, lg = lane >> 4;
; #pragma unroll
;     for (int i = 0; i < 4; i++) {
;       const int t = row0 + wm * 64 + i * 16 + lr;
; #pragma unroll
;       for (int j = 0; j < 4; j++) {
;         float4* d = (float4*)(hrow(p, b, t) + nt * 128 + wn * 64 + j * 16 + lg * 4);
;         float4 v = *d;
;         v.x += acc[i][j][0]; v.y += acc[i][j][1]; v.z += acc[i][j][2]; v.w += acc[i][j][3];
;         *d = v;
;       }
;     }
	s_waitcnt lgkmcnt(0)
	s_waitcnt vmcnt(4)
	v_mov_b32_e32 v42, v181
	s_lshl_b32 s0, s0, 7
	v_ashrrev_i32_e32 v38, 1, v42
	v_and_b32_e32 v38, 0xffffffc0, v38
	v_add_u32_e32 v38, s4, v38
	s_waitcnt vmcnt(3)
	v_and_or_b32 v46, v42, 15, v38
	s_movk_i32 s4, 0x80
	v_add_u32_e32 v40, s3, v46
	v_cmp_gt_i32_e32 vcc, s4, v46
	v_add_u32_e32 v38, 0xffffff80, v46
	v_ashrrev_i32_e32 v39, 31, v40
	v_cndmask_b32_e32 v39, 0, v39, vcc
	v_cndmask_b32_e32 v38, v38, v40, vcc
	v_mov_b32_e32 v47, s8
	v_mov_b32_e32 v48, s39
	v_mov_b32_e32 v49, s7
	s_waitcnt vmcnt(2)
	v_mov_b32_e32 v50, s60
	s_ashr_i32 s1, s0, 31
	v_cndmask_b32_e32 v41, v47, v48, vcc
	v_cndmask_b32_e32 v40, v49, v50, vcc
	v_lshlrev_b64 v[38:39], 12, v[38:39]
	v_and_b32_e32 v0, 64, v42
	v_lshl_add_u64 v[38:39], v[40:41], 0, v[38:39]
	s_lshl_b64 s[0:1], s[0:1], 2
	v_lshl_add_u64 v[38:39], v[38:39], 0, s[0:1]
	v_lshlrev_b32_e32 v0, 2, v0
	v_lshl_add_u64 v[40:41], v[38:39], 0, v[0:1]
	v_and_b32_e32 v38, 48, v42
	v_mov_b32_e32 v39, v1
	v_lshl_add_u64 v[44:45], v[40:41], 0, v[38:39]
	global_load_dwordx4 v[220:223], v[44:45], off
	global_load_dwordx4 v[224:227], v[44:45], off offset:64
	global_load_dwordx4 v[228:231], v[44:45], off offset:128
	global_load_dwordx4 v[232:235], v[44:45], off offset:192
	s_waitcnt vmcnt(3)
	v_pk_add_f32 v[220:221], v[86:87], v[220:221]
	v_pk_add_f32 v[222:223], v[88:89], v[222:223]
	global_store_dwordx4 v[44:45], v[220:223], off
	s_waitcnt vmcnt(3)
	v_pk_add_f32 v[224:225], v[82:83], v[224:225]
	v_pk_add_f32 v[226:227], v[84:85], v[226:227]
	global_store_dwordx4 v[44:45], v[224:227], off offset:64
	s_waitcnt vmcnt(3)
	v_pk_add_f32 v[228:229], v[78:79], v[228:229]
	v_pk_add_f32 v[230:231], v[80:81], v[230:231]
	global_store_dwordx4 v[44:45], v[228:231], off offset:128
	s_waitcnt vmcnt(3)
	v_pk_add_f32 v[232:233], v[74:75], v[232:233]
	v_pk_add_f32 v[234:235], v[76:77], v[234:235]
	global_store_dwordx4 v[44:45], v[232:235], off offset:192
	s_nop 1
	v_or_b32_e32 v40, 16, v46
	v_cmp_gt_i32_e32 vcc, s4, v40
	v_add_u32_e32 v40, s3, v40
	v_add_u32_e32 v42, 0xffffff90, v46
	v_ashrrev_i32_e32 v41, 31, v40
	v_cndmask_b32_e32 v41, 0, v41, vcc
	v_cndmask_b32_e32 v40, v42, v40, vcc
	v_cndmask_b32_e32 v43, v47, v48, vcc
	v_cndmask_b32_e32 v42, v49, v50, vcc
	v_lshlrev_b64 v[40:41], 12, v[40:41]
	v_lshl_add_u64 v[40:41], v[42:43], 0, v[40:41]
	v_lshl_add_u64 v[40:41], v[40:41], 0, s[0:1]
	v_lshl_add_u64 v[40:41], v[40:41], 0, v[0:1]
	v_lshl_add_u64 v[44:45], v[40:41], 0, v[38:39]
	global_load_dwordx4 v[220:223], v[44:45], off
	global_load_dwordx4 v[224:227], v[44:45], off offset:64
	global_load_dwordx4 v[228:231], v[44:45], off offset:128
	global_load_dwordx4 v[232:235], v[44:45], off offset:192
	s_waitcnt vmcnt(3)
	v_pk_add_f32 v[220:221], v[66:67], v[220:221]
	v_pk_add_f32 v[222:223], v[68:69], v[222:223]
	global_store_dwordx4 v[44:45], v[220:223], off
	s_waitcnt vmcnt(3)
	v_pk_add_f32 v[224:225], v[62:63], v[224:225]
	v_pk_add_f32 v[226:227], v[64:65], v[226:227]
	global_store_dwordx4 v[44:45], v[224:227], off offset:64
	s_waitcnt vmcnt(3)
	v_pk_add_f32 v[228:229], v[58:59], v[228:229]
	v_pk_add_f32 v[230:231], v[60:61], v[230:231]
	global_store_dwordx4 v[44:45], v[228:231], off offset:128
	s_waitcnt vmcnt(3)
	v_pk_add_f32 v[34:35], v[34:35], v[232:233]
	v_pk_add_f32 v[36:37], v[36:37], v[234:235]
	global_store_dwordx4 v[44:45], v[34:37], off offset:192
	s_nop 1
	v_or_b32_e32 v34, 32, v46
	v_cmp_gt_i32_e32 vcc, s4, v34
	v_add_u32_e32 v34, s3, v34
	v_add_u32_e32 v36, 0xffffffa0, v46
	v_ashrrev_i32_e32 v35, 31, v34
	v_cndmask_b32_e32 v35, 0, v35, vcc
	v_cndmask_b32_e32 v34, v36, v34, vcc
	v_cndmask_b32_e32 v37, v47, v48, vcc
	v_cndmask_b32_e32 v36, v49, v50, vcc
	v_lshlrev_b64 v[34:35], 12, v[34:35]
	v_lshl_add_u64 v[34:35], v[36:37], 0, v[34:35]
	v_lshl_add_u64 v[34:35], v[34:35], 0, s[0:1]
	v_lshl_add_u64 v[34:35], v[34:35], 0, v[0:1]
	v_lshl_add_u64 v[40:41], v[34:35], 0, v[38:39]
	global_load_dwordx4 v[220:223], v[40:41], off
	global_load_dwordx4 v[224:227], v[40:41], off offset:64
	global_load_dwordx4 v[228:231], v[40:41], off offset:128
	global_load_dwordx4 v[232:235], v[40:41], off offset:192
	s_waitcnt vmcnt(3)
	v_pk_add_f32 v[30:31], v[30:31], v[220:221]
	v_pk_add_f32 v[32:33], v[32:33], v[222:223]
	global_store_dwordx4 v[40:41], v[30:33], off
	s_waitcnt vmcnt(3)
	v_pk_add_f32 v[26:27], v[26:27], v[224:225]
	v_pk_add_f32 v[28:29], v[28:29], v[226:227]
	global_store_dwordx4 v[40:41], v[26:29], off offset:64
	s_waitcnt vmcnt(3)
	v_pk_add_f32 v[22:23], v[22:23], v[228:229]
	v_pk_add_f32 v[24:25], v[24:25], v[230:231]
	global_store_dwordx4 v[40:41], v[22:25], off offset:128
	s_waitcnt vmcnt(3)
	v_pk_add_f32 v[18:19], v[18:19], v[232:233]
	v_pk_add_f32 v[20:21], v[20:21], v[234:235]
	global_store_dwordx4 v[40:41], v[18:21], off offset:192
	s_nop 1
	v_or_b32_e32 v18, 48, v46
	v_cmp_gt_i32_e32 vcc, s4, v18
	v_add_u32_e32 v18, s3, v18
	v_add_u32_e32 v20, 0xffffffb0, v46
	v_ashrrev_i32_e32 v19, 31, v18
	v_cndmask_b32_e32 v19, 0, v19, vcc
	v_cndmask_b32_e32 v18, v20, v18, vcc
	v_cndmask_b32_e32 v21, v47, v48, vcc
	v_cndmask_b32_e32 v20, v49, v50, vcc
	v_lshlrev_b64 v[18:19], 12, v[18:19]
	v_lshl_add_u64 v[18:19], v[20:21], 0, v[18:19]
	v_lshl_add_u64 v[18:19], v[18:19], 0, s[0:1]
	v_lshl_add_u64 v[18:19], v[18:19], 0, v[0:1]
	v_lshl_add_u64 v[22:23], v[18:19], 0, v[38:39]
	global_load_dwordx4 v[220:223], v[22:23], off
	global_load_dwordx4 v[224:227], v[22:23], off offset:64
	global_load_dwordx4 v[228:231], v[22:23], off offset:128
	global_load_dwordx4 v[232:235], v[22:23], off offset:192
	s_waitcnt vmcnt(3)
	v_pk_add_f32 v[14:15], v[14:15], v[220:221]
	v_pk_add_f32 v[16:17], v[16:17], v[222:223]
	global_store_dwordx4 v[22:23], v[14:17], off
	s_waitcnt vmcnt(3)
	v_pk_add_f32 v[10:11], v[10:11], v[224:225]
	v_pk_add_f32 v[12:13], v[12:13], v[226:227]
	global_store_dwordx4 v[22:23], v[10:13], off offset:64
	s_waitcnt vmcnt(3)
	v_pk_add_f32 v[6:7], v[6:7], v[228:229]
	v_pk_add_f32 v[8:9], v[8:9], v[230:231]
	global_store_dwordx4 v[22:23], v[6:9], off offset:128
	s_waitcnt vmcnt(3)
	v_pk_add_f32 v[2:3], v[2:3], v[232:233]
	v_pk_add_f32 v[4:5], v[4:5], v[234:235]
	global_store_dwordx4 v[22:23], v[2:5], off offset:192
	s_branch .LBB0_1044
; #define MFMA(a, b, c) __builtin_amdgcn_mfma_f32_16x16x32_bf16(a, b, c, 0, 0, 0)
; DEV int get_tid() { int t = threadIdx.x; asm volatile("" : "+v"(t)); return t; }
; DEV f32x4 mini_gemm16(const bf16_t* __restrict__ A16, int lda, const bf16_t* __restrict__ Bt16, int ldb, int k0, int klen, int lane) {
;   const int lr = lane & 15, lg = lane >> 4;
;   const bf16_t* pa = A16 + (size_t)lr * lda + k0 + lg * 8;
;   const bf16_t* pb = Bt16 + (size_t)lr * ldb + k0 + lg * 8;
;   f32x4 acc = (f32x4){0.f, 0.f, 0.f, 0.f};
; #pragma unroll 4
;   for (int k = 0; k < klen; k += 32) {
;     bf16x8 a = *(const bf16x8*)(pa + k);
;     bf16x8 b = *(const bf16x8*)(pb + k);
;     acc = MFMA(b, a, acc);
;   }
;   return acc;
; }
; DEV void phase_resid(const Params& p, int b, const bf16_t* A, int K, const bf16_t* Wt, unsigned char* ldsraw) {
;     ...
;     if (item >= 256) {
;       const int lane = get_tid() & 63, wave = get_tid() >> 6, lr = lane & 15, lg = lane >> 4;
;       const int n0 = (item - 256) * 16;
;       f32x4* red = (f32x4*)ldsraw;
;       const int ks = K >> 3;
;       __syncthreads();
;       red[wave * 64 + lane] = mini_gemm16(A + (size_t)112 * K, K, Wt + (size_t)n0 * K, K, wave * ks, ks, lane);
;       __syncthreads();
;       if (wave == 0) {
;         f32x4 a = red[lane];
; #pragma unroll
;         for (int w = 1; w < 8; w++) a += red[w * 64 + lane];
;         float4* d = (float4*)(hrow(p, b, 112 + lr) + n0 + lg * 4);
;         float4 v = *d;
;         v.x += a[0]; v.y += a[1]; v.z += a[2]; v.w += a[3];
;         *d = v;
;       }
;       continue;
.LBB0_1049:
	s_and_b64 vcc, exec, s[0:1]
	s_cbranch_vccz .LBB0_1044
	v_mov_b32_e32 v2, v181
	v_mov_b32_e32 v20, v181
	s_lshl_b32 s0, s2, 4
	s_add_i32 s82, s0, 0xfffff000
	v_lshlrev_b32_e32 v0, 1, v20
	s_lshl_b64 s[0:1], s[82:83], 11
	v_and_b32_e32 v4, 0xffffff80, v0
	v_lshlrev_b32_e32 v0, 11, v2
	s_add_u32 s0, s14, s0
	v_and_b32_e32 v6, 0x7800, v0
	v_mov_b32_e32 v7, v1
	v_ashrrev_i32_e32 v5, 31, v4
	s_addc_u32 s1, s15, s1
	v_lshl_add_u64 v[8:9], s[16:17], 0, v[6:7]
	v_lshlrev_b64 v[4:5], 1, v[4:5]
	v_lshl_add_u64 v[8:9], v[8:9], 0, v[4:5]
	v_and_b32_e32 v0, 48, v2
	v_lshl_add_u64 v[6:7], s[0:1], 0, v[6:7]
	v_lshl_add_u64 v[16:17], v[8:9], 0, v[0:1]
	v_lshl_add_u64 v[4:5], v[6:7], 0, v[4:5]
	s_barrier
	v_lshl_add_u64 v[18:19], v[4:5], 0, v[0:1]
	global_load_dwordx4 v[60:63], v[16:17], off
	global_load_dwordx4 v[64:67], v[18:19], off
	global_load_dwordx4 v[68:71], v[16:17], off offset:64
	global_load_dwordx4 v[72:75], v[18:19], off offset:64
	global_load_dwordx4 v[76:79], v[16:17], off offset:128
	global_load_dwordx4 v[80:83], v[18:19], off offset:128
	global_load_dwordx4 v[84:87], v[16:17], off offset:192
	global_load_dwordx4 v[88:91], v[18:19], off offset:192
	v_and_b32_e32 v3, 63, v2
	v_cmp_gt_u32_e32 vcc, 64, v20
	s_waitcnt vmcnt(6)
	v_mfma_f32_16x16x32_bf16 v[4:7], v[64:67], v[60:63], 0
	s_waitcnt vmcnt(4)
	v_mfma_f32_16x16x32_bf16 v[4:7], v[72:75], v[68:71], v[4:7]
	s_waitcnt vmcnt(2)
	v_mfma_f32_16x16x32_bf16 v[4:7], v[80:83], v[76:79], v[4:7]
	s_waitcnt vmcnt(0)
	v_mfma_f32_16x16x32_bf16 v[4:7], v[88:91], v[84:87], v[4:7]
	v_and_b32_e32 v8, 0xfffffc0, v20
	v_lshlrev_b32_e32 v8, 4, v8
	v_lshlrev_b32_e32 v9, 4, v3
	v_add3_u32 v8, 0, v8, v9
	s_nop 3
	ds_write_b128 v8, v[4:7]
	s_waitcnt lgkmcnt(0)
	s_barrier
	s_and_saveexec_b64 s[0:1], vcc
	s_cbranch_execz .LBB0_1043
	v_lshl_add_u32 v3, v3, 4, 0
	ds_read_b128 v[4:7], v3
	ds_read_b128 v[8:11], v3 offset:1024
	v_lshlrev_b32_e32 v2, 12, v2
	v_and_b32_e32 v2, 0xf000, v2
	v_or_b32_e32 v2, s6, v2
	s_waitcnt lgkmcnt(0)
	v_pk_add_f32 v[10:11], v[6:7], v[10:11]
	v_pk_add_f32 v[8:9], v[4:5], v[8:9]
	ds_read_b128 v[4:7], v3 offset:2048
	s_waitcnt lgkmcnt(0)
	v_pk_add_f32 v[10:11], v[10:11], v[6:7]
	v_pk_add_f32 v[8:9], v[8:9], v[4:5]
	ds_read_b128 v[4:7], v3 offset:3072
	s_waitcnt lgkmcnt(0)
	v_pk_add_f32 v[10:11], v[10:11], v[6:7]
	v_pk_add_f32 v[8:9], v[8:9], v[4:5]
	ds_read_b128 v[4:7], v3 offset:4096
	s_waitcnt lgkmcnt(0)
	v_pk_add_f32 v[10:11], v[10:11], v[6:7]
	v_pk_add_f32 v[8:9], v[8:9], v[4:5]
	ds_read_b128 v[4:7], v3 offset:5120
	s_waitcnt lgkmcnt(0)
	v_pk_add_f32 v[10:11], v[10:11], v[6:7]
	v_pk_add_f32 v[8:9], v[8:9], v[4:5]
	ds_read_b128 v[4:7], v3 offset:6144
	s_waitcnt lgkmcnt(0)
	v_pk_add_f32 v[10:11], v[10:11], v[6:7]
	v_pk_add_f32 v[8:9], v[8:9], v[4:5]
	ds_read_b128 v[4:7], v3 offset:7168
	v_mov_b32_e32 v3, v1
	v_lshl_add_u64 v[2:3], s[92:93], 0, v[2:3]
	v_lshl_add_u64 v[2:3], s[82:83], 2, v[2:3]
	v_lshl_add_u64 v[2:3], v[2:3], 0, v[0:1]
	s_waitcnt lgkmcnt(0)
	v_pk_add_f32 v[6:7], v[10:11], v[6:7]
	v_add_co_u32_e32 v10, vcc, 0x32f0000, v2
	v_pk_add_f32 v[8:9], v[8:9], v[4:5]
	s_nop 0
	v_addc_co_u32_e32 v11, vcc, 0, v3, vcc
	global_load_dwordx4 v[2:5], v[10:11], off
	s_waitcnt vmcnt(0)
	v_pk_add_f32 v[2:3], v[2:3], v[8:9]
	v_pk_add_f32 v[4:5], v[6:7], v[4:5]
	global_store_dwordx4 v[10:11], v[2:5], off
	s_branch .LBB0_1043

; #define MFMA(a, b, c) __builtin_amdgcn_mfma_f32_16x16x32_bf16(a, b, c, 0, 0, 0)
; template <int BN, bool TRANS>
; DEV void gemm256_kstep(f32x4 (&acc)[4][BN / 32], const bf16_t* as, const bf16_t* bs, int sw) {
;   constexpr int LS = 64, NJ = BN / 32;
;   bf16x8 a[4];
; #pragma unroll
;   for (int i = 0; i < 4; i++) a[i] = *(const bf16x8*)(as + i * 16 * LS + sw);
; #pragma unroll
;   for (int j = 0; j < NJ; j++) {
;     bf16x8 bb = *(const bf16x8*)(bs + j * 16 * LS + sw);
; #pragma unroll
;     for (int i = 0; i < 4; i++) acc[i][j] = TRANS ? MFMA(a[i], bb, acc[i][j]) : MFMA(bb, a[i], acc[i][j]);
;   }
; }
; template <int BN, bool TRANS = false>
; DEV void gemm256_acc(f32x4 (&acc)[4][BN / 32], const bf16_t* __restrict__ A, int lda, int m_valid,
;                      const bf16_t* __restrict__ Bt, int ldb, int K, bf16_t* lds) {
;     ...
;   for (int kt = 0; kt < nk; kt++) {
;     const int cur = kt & 1;
;     gemm256_kstep<BN, TRANS>(acc, As + cur * A_SZ + aoff, Bs + cur * B_SZ + boff, sw0);
;     __builtin_amdgcn_sched_barrier(0);
;     LSTORE(cur ^ 1)
;     {
;       const int kn = (kt + 2 < nk) ? kt + 2 : nk - 1;
;       GLOAD(kn * 64)
;     }
;     __builtin_amdgcn_sched_barrier(0);
;     gemm256_kstep<BN, TRANS>(acc, As + cur * A_SZ + aoff, Bs + cur * B_SZ + boff, sw1);
;     __syncthreads();
;   }
.Lg128_1290:
	s_min_u32 s8, s7, 41
	s_lshl_b32 s82, s8, 7
	s_and_b32 s8, s7, 1
	v_lshl_add_u32 v204, s8, 15, v104
	v_lshl_add_u32 v205, s8, 14, v103
	v_add_u32_e32 v204, v204, v109
	v_add_u32_e32 v205, v205, v109
	s_xor_b32 s8, s8, 1
	s_lshl_b32 s9, s8, 15
	v_lshl_add_u32 v206, s8, 14, v103
	s_lshl_b32 s8, s8, 14
	s_add_i32 s8, s8, 0x10000
	s_waitcnt lgkmcnt(3)
	v_mfma_f32_16x16x32_bf16 v[86:89], v[236:239], v[110:113], v[86:89]
	v_mfma_f32_16x16x32_bf16 v[66:69], v[236:239], v[114:117], v[66:69]
	v_mfma_f32_16x16x32_bf16 v[30:33], v[236:239], v[118:121], v[30:33]
	v_mfma_f32_16x16x32_bf16 v[14:17], v[236:239], v[122:125], v[14:17]
	ds_read_b128 v[236:239], v205
	ds_read_b128 v[220:223], v204
	v_add3_u32 v252, s9, v105, v102
	s_waitcnt vmcnt(5)
	ds_write_b128 v252, v[38:41]
	v_lshl_add_u64 v[38:39], v[90:91], 0, s[82:83]
	global_load_dwordx4 v[38:41], v[38:39], off offset:256
	s_waitcnt lgkmcnt(5)
	v_mfma_f32_16x16x32_bf16 v[82:85], v[240:243], v[110:113], v[82:85]
	v_mfma_f32_16x16x32_bf16 v[62:65], v[240:243], v[114:117], v[62:65]
	v_mfma_f32_16x16x32_bf16 v[26:29], v[240:243], v[118:121], v[26:29]
	v_mfma_f32_16x16x32_bf16 v[10:13], v[240:243], v[122:125], v[10:13]
	ds_read_b128 v[240:243], v205 offset:2048
	ds_read_b128 v[224:227], v204 offset:2048
	v_add3_u32 v252, s9, v106, v102
	s_waitcnt vmcnt(5)
	ds_write_b128 v252, v[42:45]
	v_lshl_add_u64 v[42:43], v[92:93], 0, s[82:83]
	global_load_dwordx4 v[42:45], v[42:43], off offset:256
	v_add3_u32 v252, s9, v107, v102
	s_waitcnt vmcnt(5)
	ds_write_b128 v252, v[46:49]
	v_lshl_add_u64 v[46:47], v[94:95], 0, s[82:83]
	global_load_dwordx4 v[46:49], v[46:47], off offset:256
	s_waitcnt lgkmcnt(8)
	v_mfma_f32_16x16x32_bf16 v[78:81], v[244:247], v[110:113], v[78:81]
	v_mfma_f32_16x16x32_bf16 v[58:61], v[244:247], v[114:117], v[58:61]
	v_mfma_f32_16x16x32_bf16 v[22:25], v[244:247], v[118:121], v[22:25]
	v_mfma_f32_16x16x32_bf16 v[6:9], v[244:247], v[122:125], v[6:9]
	ds_read_b128 v[244:247], v205 offset:4096
	ds_read_b128 v[228:231], v204 offset:4096
	v_add3_u32 v252, s9, v108, v102
	s_waitcnt vmcnt(5)
	ds_write_b128 v252, v[50:53]
	v_lshl_add_u64 v[50:51], v[96:97], 0, s[82:83]
	global_load_dwordx4 v[50:53], v[50:51], off offset:256
	v_add3_u32 v252, s8, v105, v102
	s_waitcnt vmcnt(5)
	ds_write_b128 v252, v[54:57]
	v_lshl_add_u64 v[54:55], v[98:99], 0, s[82:83]
	global_load_dwordx4 v[54:57], v[54:55], off offset:256
	s_waitcnt lgkmcnt(11)
	v_mfma_f32_16x16x32_bf16 v[74:77], v[248:251], v[110:113], v[74:77]
	v_mfma_f32_16x16x32_bf16 v[34:37], v[248:251], v[114:117], v[34:37]
	v_mfma_f32_16x16x32_bf16 v[18:21], v[248:251], v[118:121], v[18:21]
	v_mfma_f32_16x16x32_bf16 v[2:5], v[248:251], v[122:125], v[2:5]
	ds_read_b128 v[248:251], v205 offset:6144
	ds_read_b128 v[232:235], v204 offset:6144
	v_add3_u32 v252, s8, v106, v102
	s_waitcnt vmcnt(5)
	ds_write_b128 v252, v[70:73]
	v_lshl_add_u64 v[70:71], v[100:101], 0, s[82:83]
	global_load_dwordx4 v[70:73], v[70:71], off offset:256
	v_lshlrev_b32_e32 v203, 1, v0
	v_add3_u32 v216, v104, s9, v203
	v_add_u32_e32 v206, v206, v203
	s_waitcnt lgkmcnt(0)
	s_barrier
	ds_read_b128 v[110:113], v216
	ds_read_b128 v[114:117], v216 offset:2048
	ds_read_b128 v[118:121], v216 offset:4096
	ds_read_b128 v[122:125], v216 offset:6144
	v_mfma_f32_16x16x32_bf16 v[86:89], v[236:239], v[220:223], v[86:89]
	v_mfma_f32_16x16x32_bf16 v[66:69], v[236:239], v[224:227], v[66:69]
	v_mfma_f32_16x16x32_bf16 v[30:33], v[236:239], v[228:231], v[30:33]
	v_mfma_f32_16x16x32_bf16 v[14:17], v[236:239], v[232:235], v[14:17]
	ds_read_b128 v[236:239], v206
	v_mfma_f32_16x16x32_bf16 v[82:85], v[240:243], v[220:223], v[82:85]
	v_mfma_f32_16x16x32_bf16 v[62:65], v[240:243], v[224:227], v[62:65]
	v_mfma_f32_16x16x32_bf16 v[26:29], v[240:243], v[228:231], v[26:29]
	v_mfma_f32_16x16x32_bf16 v[10:13], v[240:243], v[232:235], v[10:13]
	ds_read_b128 v[240:243], v206 offset:2048
	v_mfma_f32_16x16x32_bf16 v[78:81], v[244:247], v[220:223], v[78:81]
	v_mfma_f32_16x16x32_bf16 v[58:61], v[244:247], v[224:227], v[58:61]
	v_mfma_f32_16x16x32_bf16 v[22:25], v[244:247], v[228:231], v[22:25]
	v_mfma_f32_16x16x32_bf16 v[6:9], v[244:247], v[232:235], v[6:9]
	ds_read_b128 v[244:247], v206 offset:4096
	v_mfma_f32_16x16x32_bf16 v[74:77], v[248:251], v[220:223], v[74:77]
	v_mfma_f32_16x16x32_bf16 v[34:37], v[248:251], v[224:227], v[34:37]
	v_mfma_f32_16x16x32_bf16 v[18:21], v[248:251], v[228:231], v[18:21]
	v_mfma_f32_16x16x32_bf16 v[2:5], v[248:251], v[232:235], v[2:5]
	ds_read_b128 v[248:251], v206 offset:6144
	s_add_i32 s7, s7, 1
	s_cmp_lg_u32 s7, 44
	s_cbranch_scc1 .Lg128_1290
; DEV int get_tid() { int t = threadIdx.x; asm volatile("" : "+v"(t)); return t; }
; DEV float* hrow(const Params& p, int b, int t) {
;   return (t < 128) ? (float*)(p.ws + OFF_H) + (size_t)(b * 128 + t) * 1024 : p.out + ((size_t)b * 8192 + (t - 128)) * 1024;
; DEV void phase_resid(const Params& p, int b, const bf16_t* A, int K, const bf16_t* Wt, unsigned char* ldsraw) {
;     ...
;     const int tid = get_tid(), lane = tid & 63, wave = tid >> 6, wm = wave >> 1, wn = wave & 1; const int lr = lane & 15, lg = lane >> 4;
; #pragma unroll
;     for (int i = 0; i < 4; i++) {
;       const int t = row0 + wm * 64 + i * 16 + lr;
; #pragma unroll
;       for (int j = 0; j < 4; j++) {
;         float4* d = (float4*)(hrow(p, b, t) + nt * 128 + wn * 64 + j * 16 + lg * 4);
;         float4 v = *d;
;         v.x += acc[i][j][0]; v.y += acc[i][j][1]; v.z += acc[i][j][2]; v.w += acc[i][j][3];
;         *d = v;
;       }
;     }
	s_waitcnt lgkmcnt(0)
	s_waitcnt vmcnt(4)
	v_mov_b32_e32 v42, v181
	s_lshl_b32 s0, s0, 7
	v_ashrrev_i32_e32 v38, 1, v42
	v_and_b32_e32 v38, 0xffffffc0, v38
	v_add_u32_e32 v38, s1, v38
	s_waitcnt vmcnt(3)
	v_and_or_b32 v46, v42, 15, v38
	v_add_u32_e32 v40, s3, v46
	v_cmp_gt_i32_e32 vcc, s52, v46
	v_add_u32_e32 v38, 0xffffff80, v46
	v_ashrrev_i32_e32 v39, 31, v40
	v_cndmask_b32_e32 v39, 0, v39, vcc
	v_cndmask_b32_e32 v38, v38, v40, vcc
	v_mov_b32_e32 v47, s6
	v_mov_b32_e32 v48, s39
	v_mov_b32_e32 v49, s5
	s_waitcnt vmcnt(2)
	v_mov_b32_e32 v50, s60
	s_ashr_i32 s1, s0, 31
	v_cndmask_b32_e32 v41, v47, v48, vcc
	v_cndmask_b32_e32 v40, v49, v50, vcc
	v_lshlrev_b64 v[38:39], 12, v[38:39]
	v_and_b32_e32 v0, 64, v42
	v_lshl_add_u64 v[38:39], v[40:41], 0, v[38:39]
	s_lshl_b64 s[0:1], s[0:1], 2
	v_lshl_add_u64 v[38:39], v[38:39], 0, s[0:1]
	v_lshlrev_b32_e32 v0, 2, v0
	v_lshl_add_u64 v[40:41], v[38:39], 0, v[0:1]
	v_and_b32_e32 v38, 48, v42
	v_mov_b32_e32 v39, v1
	v_lshl_add_u64 v[44:45], v[40:41], 0, v[38:39]
	global_load_dwordx4 v[220:223], v[44:45], off
	global_load_dwordx4 v[224:227], v[44:45], off offset:64
	global_load_dwordx4 v[228:231], v[44:45], off offset:128
	global_load_dwordx4 v[232:235], v[44:45], off offset:192
	s_waitcnt vmcnt(3)
	v_pk_add_f32 v[220:221], v[86:87], v[220:221]
	v_pk_add_f32 v[222:223], v[88:89], v[222:223]
	global_store_dwordx4 v[44:45], v[220:223], off
	s_waitcnt vmcnt(3)
	v_pk_add_f32 v[224:225], v[82:83], v[224:225]
	v_pk_add_f32 v[226:227], v[84:85], v[226:227]
	global_store_dwordx4 v[44:45], v[224:227], off offset:64
	s_waitcnt vmcnt(3)
	v_pk_add_f32 v[228:229], v[78:79], v[228:229]
	v_pk_add_f32 v[230:231], v[80:81], v[230:231]
	global_store_dwordx4 v[44:45], v[228:231], off offset:128
	s_waitcnt vmcnt(3)
	v_pk_add_f32 v[232:233], v[74:75], v[232:233]
	v_pk_add_f32 v[234:235], v[76:77], v[234:235]
	global_store_dwordx4 v[44:45], v[232:235], off offset:192
	s_nop 1
	v_or_b32_e32 v40, 16, v46
	v_cmp_gt_i32_e32 vcc, s52, v40
	v_add_u32_e32 v40, s3, v40
	v_add_u32_e32 v42, 0xffffff90, v46
	v_ashrrev_i32_e32 v41, 31, v40
	v_cndmask_b32_e32 v41, 0, v41, vcc
	v_cndmask_b32_e32 v40, v42, v40, vcc
	v_cndmask_b32_e32 v43, v47, v48, vcc
	v_cndmask_b32_e32 v42, v49, v50, vcc
	v_lshlrev_b64 v[40:41], 12, v[40:41]
	v_lshl_add_u64 v[40:41], v[42:43], 0, v[40:41]
	v_lshl_add_u64 v[40:41], v[40:41], 0, s[0:1]
	v_lshl_add_u64 v[40:41], v[40:41], 0, v[0:1]
	v_lshl_add_u64 v[44:45], v[40:41], 0, v[38:39]
	global_load_dwordx4 v[220:223], v[44:45], off
	global_load_dwordx4 v[224:227], v[44:45], off offset:64
	global_load_dwordx4 v[228:231], v[44:45], off offset:128
	global_load_dwordx4 v[232:235], v[44:45], off offset:192
	s_waitcnt vmcnt(3)
	v_pk_add_f32 v[220:221], v[66:67], v[220:221]
	v_pk_add_f32 v[222:223], v[68:69], v[222:223]
	global_store_dwordx4 v[44:45], v[220:223], off
	s_waitcnt vmcnt(3)
	v_pk_add_f32 v[224:225], v[62:63], v[224:225]
	v_pk_add_f32 v[226:227], v[64:65], v[226:227]
	global_store_dwordx4 v[44:45], v[224:227], off offset:64
	s_waitcnt vmcnt(3)
	v_pk_add_f32 v[228:229], v[58:59], v[228:229]
	v_pk_add_f32 v[230:231], v[60:61], v[230:231]
	global_store_dwordx4 v[44:45], v[228:231], off offset:128
	s_waitcnt vmcnt(3)
	v_pk_add_f32 v[34:35], v[34:35], v[232:233]
	v_pk_add_f32 v[36:37], v[36:37], v[234:235]
	global_store_dwordx4 v[44:45], v[34:37], off offset:192
	s_nop 1
	v_or_b32_e32 v34, 32, v46
	v_cmp_gt_i32_e32 vcc, s52, v34
	v_add_u32_e32 v34, s3, v34
	v_add_u32_e32 v36, 0xffffffa0, v46
	v_ashrrev_i32_e32 v35, 31, v34
	v_cndmask_b32_e32 v35, 0, v35, vcc
	v_cndmask_b32_e32 v34, v36, v34, vcc
	v_cndmask_b32_e32 v37, v47, v48, vcc
	v_cndmask_b32_e32 v36, v49, v50, vcc
	v_lshlrev_b64 v[34:35], 12, v[34:35]
	v_lshl_add_u64 v[34:35], v[36:37], 0, v[34:35]
	v_lshl_add_u64 v[34:35], v[34:35], 0, s[0:1]
	v_lshl_add_u64 v[34:35], v[34:35], 0, v[0:1]
	v_lshl_add_u64 v[40:41], v[34:35], 0, v[38:39]
	global_load_dwordx4 v[220:223], v[40:41], off
	global_load_dwordx4 v[224:227], v[40:41], off offset:64
	global_load_dwordx4 v[228:231], v[40:41], off offset:128
	global_load_dwordx4 v[232:235], v[40:41], off offset:192
	s_waitcnt vmcnt(3)
	v_pk_add_f32 v[30:31], v[30:31], v[220:221]
	v_pk_add_f32 v[32:33], v[32:33], v[222:223]
	global_store_dwordx4 v[40:41], v[30:33], off
	s_waitcnt vmcnt(3)
	v_pk_add_f32 v[26:27], v[26:27], v[224:225]
	v_pk_add_f32 v[28:29], v[28:29], v[226:227]
	global_store_dwordx4 v[40:41], v[26:29], off offset:64
	s_waitcnt vmcnt(3)
	v_pk_add_f32 v[22:23], v[22:23], v[228:229]
	v_pk_add_f32 v[24:25], v[24:25], v[230:231]
	global_store_dwordx4 v[40:41], v[22:25], off offset:128
	s_waitcnt vmcnt(3)
	v_pk_add_f32 v[18:19], v[18:19], v[232:233]
	v_pk_add_f32 v[20:21], v[20:21], v[234:235]
	global_store_dwordx4 v[40:41], v[18:21], off offset:192
	s_nop 1
	v_or_b32_e32 v18, 48, v46
	v_cmp_gt_i32_e32 vcc, s52, v18
	v_add_u32_e32 v18, s3, v18
	v_add_u32_e32 v20, 0xffffffb0, v46
	v_ashrrev_i32_e32 v19, 31, v18
	v_cndmask_b32_e32 v19, 0, v19, vcc
	v_cndmask_b32_e32 v18, v20, v18, vcc
	v_cndmask_b32_e32 v21, v47, v48, vcc
	v_cndmask_b32_e32 v20, v49, v50, vcc
	v_lshlrev_b64 v[18:19], 12, v[18:19]
	v_lshl_add_u64 v[18:19], v[20:21], 0, v[18:19]
	v_lshl_add_u64 v[18:19], v[18:19], 0, s[0:1]
	v_lshl_add_u64 v[18:19], v[18:19], 0, v[0:1]
	v_lshl_add_u64 v[22:23], v[18:19], 0, v[38:39]
	global_load_dwordx4 v[220:223], v[22:23], off
	global_load_dwordx4 v[224:227], v[22:23], off offset:64
	global_load_dwordx4 v[228:231], v[22:23], off offset:128
	global_load_dwordx4 v[232:235], v[22:23], off offset:192
	s_waitcnt vmcnt(3)
	v_pk_add_f32 v[14:15], v[14:15], v[220:221]
	v_pk_add_f32 v[16:17], v[16:17], v[222:223]
	global_store_dwordx4 v[22:23], v[14:17], off
	s_waitcnt vmcnt(3)
	v_pk_add_f32 v[10:11], v[10:11], v[224:225]
	v_pk_add_f32 v[12:13], v[12:13], v[226:227]
	global_store_dwordx4 v[22:23], v[10:13], off offset:64
	s_waitcnt vmcnt(3)
	v_pk_add_f32 v[6:7], v[6:7], v[228:229]
	v_pk_add_f32 v[8:9], v[8:9], v[230:231]
	global_store_dwordx4 v[22:23], v[6:9], off offset:128
	s_waitcnt vmcnt(3)
	v_pk_add_f32 v[2:3], v[2:3], v[232:233]
	v_pk_add_f32 v[4:5], v[4:5], v[234:235]
	global_store_dwordx4 v[22:23], v[2:5], off offset:192
	s_branch .LBB0_1287
; #define MFMA(a, b, c) __builtin_amdgcn_mfma_f32_16x16x32_bf16(a, b, c, 0, 0, 0)
; DEV int get_tid() { int t = threadIdx.x; asm volatile("" : "+v"(t)); return t; }
; DEV f32x4 mini_gemm16(const bf16_t* __restrict__ A16, int lda, const bf16_t* __restrict__ Bt16, int ldb, int k0, int klen, int lane) {
;   const int lr = lane & 15, lg = lane >> 4;
;   const bf16_t* pa = A16 + (size_t)lr * lda + k0 + lg * 8;
;   const bf16_t* pb = Bt16 + (size_t)lr * ldb + k0 + lg * 8;
;   f32x4 acc = (f32x4){0.f, 0.f, 0.f, 0.f};
; #pragma unroll 4
;   for (int k = 0; k < klen; k += 32) {
;     bf16x8 a = *(const bf16x8*)(pa + k);
;     bf16x8 b = *(const bf16x8*)(pb + k);
;     acc = MFMA(b, a, acc);
;   }
;   return acc;
; }
; DEV void phase_resid(const Params& p, int b, const bf16_t* A, int K, const bf16_t* Wt, unsigned char* ldsraw) {
;     ...
;     if (item >= 256) {
;       const int lane = get_tid() & 63, wave = get_tid() >> 6, lr = lane & 15, lg = lane >> 4;
;       const int n0 = (item - 256) * 16;
;       f32x4* red = (f32x4*)ldsraw;
;       const int ks = K >> 3;
;       __syncthreads();
;       red[wave * 64 + lane] = mini_gemm16(A + (size_t)112 * K, K, Wt + (size_t)n0 * K, K, wave * ks, ks, lane);
;       __syncthreads();
;       if (wave == 0) {
;         f32x4 a = red[lane];
; #pragma unroll
;         for (int w = 1; w < 8; w++) a += red[w * 64 + lane];
;         float4* d = (float4*)(hrow(p, b, 112 + lr) + n0 + lg * 4);
;         float4 v = *d;
;         v.x += a[0]; v.y += a[1]; v.z += a[2]; v.w += a[3];
;         *d = v;
;       }
;       continue;
.LBB0_1292:
	s_and_b64 vcc, exec, s[0:1]
	s_cbranch_vccz .LBB0_1287
	v_mov_b32_e32 v2, v181
	s_waitcnt vmcnt(5)
	v_mov_b32_e32 v20, v181
	s_lshl_b32 s0, s2, 4
	v_ashrrev_i32_e32 v0, 6, v20
	s_movk_i32 s7, 0x160
	s_add_i32 s82, s0, 0xfffff000
	v_mul_lo_u32 v4, v0, s7
	v_and_b32_e32 v0, 15, v2
	s_mul_i32 s0, s82, 0x1600
	v_mul_u32_u24_e32 v0, 0xb00, v0
	s_mul_hi_u32 s1, s82, 0x1600
	s_add_u32 s0, s12, s0
	v_lshlrev_b32_e32 v6, 1, v0
	v_mov_b32_e32 v7, v1
	v_ashrrev_i32_e32 v5, 31, v4
	s_addc_u32 s1, s13, s1
	v_lshl_add_u64 v[8:9], s[14:15], 0, v[6:7]
	v_lshlrev_b64 v[4:5], 1, v[4:5]
	v_lshl_add_u64 v[8:9], v[8:9], 0, v[4:5]
	v_and_b32_e32 v0, 48, v2
	v_lshl_add_u64 v[6:7], s[0:1], 0, v[6:7]
	v_lshl_add_u64 v[16:17], v[8:9], 0, v[0:1]
	v_lshl_add_u64 v[4:5], v[6:7], 0, v[4:5]
	s_barrier
	v_lshl_add_u64 v[18:19], v[4:5], 0, v[0:1]
	global_load_dwordx4 v[60:63], v[16:17], off
	global_load_dwordx4 v[64:67], v[18:19], off
	global_load_dwordx4 v[68:71], v[16:17], off offset:64
	global_load_dwordx4 v[72:75], v[18:19], off offset:64
	global_load_dwordx4 v[76:79], v[16:17], off offset:128
	global_load_dwordx4 v[80:83], v[18:19], off offset:128
	global_load_dwordx4 v[84:87], v[16:17], off offset:192
	global_load_dwordx4 v[88:91], v[18:19], off offset:192
	global_load_dwordx4 v[92:95], v[16:17], off offset:256
	global_load_dwordx4 v[96:99], v[18:19], off offset:256
	global_load_dwordx4 v[100:103], v[16:17], off offset:320
	global_load_dwordx4 v[104:107], v[18:19], off offset:320
	global_load_dwordx4 v[108:111], v[16:17], off offset:384
	global_load_dwordx4 v[112:115], v[18:19], off offset:384
	global_load_dwordx4 v[116:119], v[16:17], off offset:448
	global_load_dwordx4 v[120:123], v[18:19], off offset:448
	global_load_dwordx4 v[124:127], v[16:17], off offset:512
	global_load_dwordx4 v[128:131], v[18:19], off offset:512
	global_load_dwordx4 v[132:135], v[16:17], off offset:576
	global_load_dwordx4 v[136:139], v[18:19], off offset:576
	global_load_dwordx4 v[140:143], v[16:17], off offset:640
	global_load_dwordx4 v[144:147], v[18:19], off offset:640
	v_and_b32_e32 v3, 63, v2
	v_cmp_gt_u32_e32 vcc, 64, v20
	s_waitcnt vmcnt(20)
	v_mfma_f32_16x16x32_bf16 v[4:7], v[64:67], v[60:63], 0
	s_waitcnt vmcnt(18)
	v_mfma_f32_16x16x32_bf16 v[4:7], v[72:75], v[68:71], v[4:7]
	s_waitcnt vmcnt(16)
	v_mfma_f32_16x16x32_bf16 v[4:7], v[80:83], v[76:79], v[4:7]
	s_waitcnt vmcnt(14)
	v_mfma_f32_16x16x32_bf16 v[4:7], v[88:91], v[84:87], v[4:7]
	s_waitcnt vmcnt(12)
	v_mfma_f32_16x16x32_bf16 v[4:7], v[96:99], v[92:95], v[4:7]
	s_waitcnt vmcnt(10)
	v_mfma_f32_16x16x32_bf16 v[4:7], v[104:107], v[100:103], v[4:7]
	s_waitcnt vmcnt(8)
	v_mfma_f32_16x16x32_bf16 v[4:7], v[112:115], v[108:111], v[4:7]
	s_waitcnt vmcnt(6)
	v_mfma_f32_16x16x32_bf16 v[4:7], v[120:123], v[116:119], v[4:7]
	s_waitcnt vmcnt(4)
	v_mfma_f32_16x16x32_bf16 v[4:7], v[128:131], v[124:127], v[4:7]
	s_waitcnt vmcnt(2)
	v_mfma_f32_16x16x32_bf16 v[4:7], v[136:139], v[132:135], v[4:7]
	s_waitcnt vmcnt(0)
	v_mfma_f32_16x16x32_bf16 v[4:7], v[144:147], v[140:143], v[4:7]
	v_and_b32_e32 v8, 0xfffffc0, v20
	v_lshlrev_b32_e32 v8, 4, v8
	v_lshlrev_b32_e32 v9, 4, v3
	v_add3_u32 v8, 0, v8, v9
	s_nop 3
	ds_write_b128 v8, v[4:7]
	s_waitcnt lgkmcnt(0)
	s_barrier
	s_and_saveexec_b64 s[0:1], vcc
	s_cbranch_execz .LBB0_1286
	v_lshl_add_u32 v3, v3, 4, 0
	ds_read_b128 v[4:7], v3
	ds_read_b128 v[8:11], v3 offset:1024
	v_lshlrev_b32_e32 v2, 12, v2
	v_and_b32_e32 v2, 0xf000, v2
	v_or_b32_e32 v2, s4, v2
	s_waitcnt lgkmcnt(0)
	v_pk_add_f32 v[10:11], v[6:7], v[10:11]
	v_pk_add_f32 v[8:9], v[4:5], v[8:9]
	ds_read_b128 v[4:7], v3 offset:2048
	s_waitcnt lgkmcnt(0)
	v_pk_add_f32 v[10:11], v[10:11], v[6:7]
	v_pk_add_f32 v[8:9], v[8:9], v[4:5]
	ds_read_b128 v[4:7], v3 offset:3072
	s_waitcnt lgkmcnt(0)
	v_pk_add_f32 v[10:11], v[10:11], v[6:7]
	v_pk_add_f32 v[8:9], v[8:9], v[4:5]
	ds_read_b128 v[4:7], v3 offset:4096
	s_waitcnt lgkmcnt(0)
	v_pk_add_f32 v[10:11], v[10:11], v[6:7]
	v_pk_add_f32 v[8:9], v[8:9], v[4:5]
	ds_read_b128 v[4:7], v3 offset:5120
	s_waitcnt lgkmcnt(0)
	v_pk_add_f32 v[10:11], v[10:11], v[6:7]
	v_pk_add_f32 v[8:9], v[8:9], v[4:5]
	ds_read_b128 v[4:7], v3 offset:6144
	s_waitcnt lgkmcnt(0)
	v_pk_add_f32 v[10:11], v[10:11], v[6:7]
	v_pk_add_f32 v[8:9], v[8:9], v[4:5]
	ds_read_b128 v[4:7], v3 offset:7168
	v_mov_b32_e32 v3, v1
	v_lshl_add_u64 v[2:3], s[92:93], 0, v[2:3]
	v_lshl_add_u64 v[2:3], s[82:83], 2, v[2:3]
	v_lshl_add_u64 v[2:3], v[2:3], 0, v[0:1]
	s_waitcnt lgkmcnt(0)
	v_pk_add_f32 v[6:7], v[10:11], v[6:7]
	v_add_co_u32_e32 v10, vcc, 0x32f0000, v2
	v_pk_add_f32 v[8:9], v[8:9], v[4:5]
	s_nop 0
	v_addc_co_u32_e32 v11, vcc, 0, v3, vcc
	global_load_dwordx4 v[2:5], v[10:11], off
	s_waitcnt vmcnt(0)
	v_pk_add_f32 v[2:3], v[2:3], v[8:9]
	v_pk_add_f32 v[4:5], v[6:7], v[4:5]
	global_store_dwordx4 v[10:11], v[2:5], off
	s_branch .LBB0_1286
